# gate|up phase: tiles and weight-conversion re-split (160 WGs x6 tiles, 32 x5, 64 x4 + whole conversion slot) so the converting workgroups no longer overrun the last GEMM round; plus K-loop changes
# baseline (speedup 1.0000x reference)
;     __device__ __forceinline__ bool next(int i, Unit& u) const { if (!StaticOrder::next(i / 3, u)) return false; u.aux = i % 3; return true; }
;     __host__ __device__ __forceinline__ bool next(int i, Unit& u) const {
;         const long L = (long)i * G + c; if (L >= nwg) return false;
;         int wgid = (int)L; { const int q = nwg / NXCD, r = nwg % NXCD, xcd = wgid % NXCD, off = wgid / NXCD; wgid = (xcd < r ? xcd * (q + 1) : r * (q + 1) + (xcd - r) * q) + off; }
;         const int nig = WGM * nN, gid = wgid / nig, fm = gid * WGM, gsz = (nM - fm) < WGM ? (nM - fm) : WGM;
;         u.pm = fm + ((wgid % nig) % gsz); u.pn = (wgid % nig) / gsz; u.aux = 0; return true;
;     }
.LBB0_298:
	s_add_i32 s55, s55, 1
	s_mul_i32 s0, s55, s54
	s_mul_hi_u32 s1, s55, s26
	s_add_i32 s1, s1, s0
	s_mul_i32 s0, s55, s26
	s_add_u32 s28, s0, s2
	s_addc_u32 s29, s1, s27
	s_cmp_lt_u32 s55, 4
	s_cbranch_scc1 .Lrb1_ok
	s_mov_b32 s28, 0x7fff0000
	s_mov_b32 s29, 0
	s_cmp_eq_u32 s55, 4
	s_cbranch_scc0 .Lrb1_r5
	s_cmp_lt_u32 s2, 0xc0
	s_cbranch_scc0 .Lrb1_ok
	s_add_i32 s28, s2, 0x400
	s_branch .Lrb1_ok
.Lrb1_r5:
	s_cmp_eq_u32 s55, 5
	s_cbranch_scc0 .Lrb1_ok
	s_cmp_lt_u32 s2, 0xa0
	s_cbranch_scc0 .Lrb1_ok
	s_add_i32 s28, s2, 0x4c0
.Lrb1_ok:
	v_mov_b64_e32 v[4:5], 0x560
	v_cmp_lt_i64_e64 s[0:1], s[28:29], v[4:5]
	v_mov_b64_e32 v[4:5], 0x55f
	v_cmp_gt_i64_e32 vcc, s[28:29], v[4:5]
	s_cbranch_vccnz .LBB0_300
	s_ashr_i32 s10, s28, 31
	s_lshr_b32 s10, s10, 29
	s_add_i32 s10, s28, s10
	s_ashr_i32 s11, s10, 3
	s_and_b32 s10, s10, -8
	s_sub_i32 s10, s28, s10
	s_cmp_lt_i32 s10, 0
	s_movk_i32 s12, 0xad
	s_cselect_b32 s12, s12, 0xac
	s_mul_i32 s10, s10, s12
	s_add_i32 s10, s10, s11
	s_mul_hi_i32 s11, s10, 0x2fa0be83
	s_lshr_b32 s12, s11, 31
	s_ashr_i32 s11, s11, 6
	s_add_i32 s11, s11, s12
	s_lshl_b32 s12, s11, 3
	s_sub_i32 s13, 32, s12
	s_min_i32 s13, s13, 8
	s_abs_i32 s28, s13
	v_cvt_f32_u32_e32 v4, s28
	s_sub_i32 s30, 0, s28
	s_mulk_i32 s11, 0x158
	s_sub_i32 s11, s10, s11
	v_rcp_iflag_f32_e32 v4, v4
	s_abs_i32 s10, s11
	s_xor_b32 s29, s11, s13
	s_ashr_i32 s29, s29, 31
	v_mul_f32_e32 v4, 0x4f7ffffe, v4
	v_cvt_u32_f32_e32 v4, v4
	s_nop 0
	v_readfirstlane_b32 s31, v4
	s_mul_i32 s30, s30, s31
	s_mul_hi_u32 s30, s31, s30
	s_add_i32 s31, s31, s30
	s_mul_hi_u32 s30, s10, s31
	s_mul_i32 s31, s30, s28
	s_sub_i32 s10, s10, s31
	s_add_i32 s40, s30, 1
	s_sub_i32 s31, s10, s28
	s_cmp_ge_u32 s10, s28
	s_cselect_b32 s30, s40, s30
	s_cselect_b32 s10, s31, s10
	s_add_i32 s31, s30, 1
	s_cmp_ge_u32 s10, s28
	s_cselect_b32 s10, s31, s30
	s_xor_b32 s10, s10, s29
	s_sub_i32 s10, s10, s29
	s_mul_i32 s13, s10, s13
	s_sub_i32 s11, s11, s13
	s_add_i32 s12, s12, s11

; #define LAS __attribute__((address_space(3)))
; #define KP() ({ KArgs kp_ = kp0; asm volatile("" : "+s"(kp_)); kp_; })
; #define G_ ({ int g__ = (int)gridDim.x; asm volatile("" : "+s"(g__)); g__; })
; #define c_ ({ int c__ = (int)blockIdx.x; asm volatile("" : "+s"(c__)); c__; })
; template <class KA> __device__ __forceinline__ void convert_range(KA a, LAS unsigned char* lds, int t_lo, int t_hi, int rank, int nrank) {
;     int tid_ = threadIdx.x; asm volatile("" : "+v"(tid_));
;     const int lane = tid_ & 63, wave = __builtin_amdgcn_readfirstlane(tid_ >> 6); LAS unsigned short* tl = (LAS unsigned short*)(lds + wave * 16384);
;     const int stride = nrank * 8; int it = t_lo + rank * 8 + wave;
;     if (it >= t_hi) return;
; __global__ void __launch_bounds__(512, 2) mega(MegaArgs a) {
;     ...
;             { const int rem = ((T_SEQ / 256) * (NGU / 256)) % G_, q = 3 * l + (half ? 2 : 0), hi = cvt_slot_hi(q) < CVT_TOTAL ? cvt_slot_hi(q) : CVT_TOTAL;
;               if (!(hf & 2) && rem && c_ >= rem && cvt_slot_lo(q) < hi) { KArgs kq = KP(); convert_range(kq, lds, cvt_slot_lo(q), hi, c_ - rem, G_ - rem); } }
.LBB0_308:
	s_mov_b32 s0, s21
	s_abs_i32 s0, s0
	v_cvt_f32_u32_e32 v1, s0
	s_sub_i32 s1, 0, s0
	v_rcp_iflag_f32_e32 v1, v1
	s_nop 0
	v_mul_f32_e32 v1, 0x4f7ffffe, v1
	v_cvt_u32_f32_e32 v1, v1
	s_nop 0
	v_readfirstlane_b32 s2, v1
	s_mul_i32 s1, s1, s2
	s_mul_hi_u32 s1, s2, s1
	s_add_i32 s2, s2, s1
	s_mul_hi_u32 s1, s2, 0x560
	s_mul_i32 s1, s1, s0
	s_sub_i32 s1, 0x560, s1
	s_sub_i32 s2, s1, s0
	s_cmp_ge_u32 s1, s0
	s_cselect_b32 s1, s2, s1
	s_sub_i32 s2, s1, s0
	s_cmp_ge_u32 s1, s0
	v_readlane_b32 s0, v251, 24
	s_cselect_b32 s44, s2, s1
	s_movk_i32 s44, 0xc0
	s_bitcmp1_b32 s0, 1
	s_cselect_b64 s[0:1], -1, 0
	s_cmp_eq_u32 s44, 0
	s_cselect_b64 s[4:5], -1, 0
	s_or_b64 s[0:1], s[0:1], s[4:5]
	s_and_b64 vcc, exec, s[0:1]
	s_cbranch_vccnz .LBB0_496
	v_readlane_b32 s0, v251, 22
	v_readlane_b32 s1, v251, 23
	s_mul_i32 s0, s0, 3
	s_lshl_b32 s1, s52, 1
	s_add_i32 s1, s1, s0
	s_mul_hi_i32 s0, s1, 0x55555556
	s_lshr_b32 s2, s0, 31
	s_add_i32 s0, s0, s2
	s_mul_i32 s2, s0, 3
	s_sub_i32 s1, s1, s2
	s_cmp_eq_u32 s1, 1
	s_movk_i32 s2, 0x2580
	s_movk_i32 s4, 0x1ce8
	s_cselect_b32 s2, s2, 0x4268
	s_cselect_b32 s4, s4, 0x2580
	s_cmp_lg_u32 s1, 0
	s_mulk_i32 s0, 0x67e8
	s_cselect_b32 s1, s2, 0
	s_add_i32 s2, s0, s1
	s_addk_i32 s2, 0x2200
	s_add_i32 s0, s2, s4
	s_min_i32 s26, s0, 0x1a500
	s_mov_b32 s0, s67
	s_cmp_ge_i32 s0, s44
	s_cselect_b64 s[0:1], -1, 0
	s_cmp_lt_i32 s2, s26
	s_cselect_b64 s[4:5], -1, 0
	s_and_b64 s[0:1], s[0:1], s[4:5]
	s_andn2_b64 vcc, exec, s[0:1]
	s_cbranch_vccnz .LBB0_496
	s_mov_b64 s[0:1], s[70:71]
	s_mov_b32 s4, s67
	s_sub_i32 s4, s4, s44
	s_mov_b32 s45, s21
	v_mov_b32_e32 v1, v0
	s_lshl_b32 s4, s4, 3
	v_readfirstlane_b32 s47, v1
	s_ashr_i32 s46, s47, 6
	s_add_i32 s2, s4, s2
	s_add_i32 s27, s2, s46
	s_cmp_ge_i32 s27, s26
	s_cbranch_scc1 .LBB0_496
	s_mul_hi_i32 s2, s27, 0x9baade8f
	s_add_i32 s2, s2, s27
	s_load_dwordx2 s[4:5], s[0:1], 0xd8
	s_waitcnt lgkmcnt(0)
	s_lshr_b32 s6, s2, 31
	s_ashr_i32 s2, s2, 14
	s_add_i32 s30, s2, s6
	s_mul_i32 s42, s30, 0xffff96c0
	s_add_i32 s42, s42, s27
	s_add_u32 s53, s4, 0x200000
	s_addc_u32 s54, s5, 0
	s_ashr_i32 s31, s30, 31
	s_mul_i32 s4, s30, 0xd300000
	s_mul_hi_i32 s2, s30, 0xd300000
	s_add_u32 s28, s53, s4
	s_addc_u32 s29, s54, s2
	s_cmpk_gt_i32 s42, 0x157f
	s_mov_b64 s[40:41], -1
	s_cbranch_scc0 .LBB0_321
	s_cmpk_gt_u32 s42, 0x203f
	s_cbranch_scc1 .LBB0_313
	s_getpc_b64 s[98:99]
